# MIXA: static rebalance of conv wave jobs (CUs 0-23 and 220-251 hand their regular jobs to pairs 48..271)
# baseline (speedup 1.0000x reference)
; #define LAS __attribute__((address_space(3)))
; __device__ __forceinline__ void mix_a_wave_jobs(Frame& F, int l) {
;     const int lane = F.lane, wave = F.wave, gi = wave & 3, c0 = 128 * gi + 2 * lane;
;     const bf16_t* U = (const bf16_t*)(F.ws + WS_U); bf16_t* YAB = (bf16_t*)(F.ws + WS_YAB);
;     const float* cw = F.in[I_CAW] + (size_t)l * 31 * DA;
;     f32x2 w[31];
; #pragma unroll
;     for (int k = 0; k < 31; ++k) w[k] = *(const f32x2*)(cw + k * DA + c0);
;     const f32x2 cbv = *(const f32x2*)(F.in[I_CAB] + l * DA + c0), lgv = *(const f32x2*)(F.in[I_LNG] + l * DA + c0), lbv = *(const f32x2*)(F.in[I_LNB] + l * DA + c0);
;     LAS f32x2* red = (LAS f32x2*)(F.lds + LDS_ARED + wave * 128);
;     for (int tb = 511 - ((int)blockIdx.x * 2 + (wave >> 2)); tb < 1096; tb += 512) {
;         f32x2 a[16];
; #pragma unroll
;         for (int t = 0; t < 16; ++t) a[t] = cbv;
;         int rowbase;
;         if (tb < 1032) {
.LBB0_267:
	v_readlane_b32 s2, v253, 12
	v_readlane_b32 s3, v253, 13
	s_waitcnt vmcnt(3)
	v_mov_b32_e32 v0, v170
	s_andn2_b64 vcc, exec, s[2:3]
	s_cbranch_vccnz .LBB0_278
	s_load_dwordx8 s[8:15], s[0:1], 0x60
	s_waitcnt vmcnt(2)
	v_lshlrev_b32_e32 v1, 1, v0
	v_readlane_b32 s16, v254, 59
	v_and_b32_e32 v75, 0x7e, v1
	v_readlane_b32 s2, v253, 9
	v_readlane_b32 s17, v254, 60
	s_mul_hi_u32 s3, s16, 0xf800
	v_or_b32_e32 v74, s2, v75
	s_mul_i32 s2, s17, 0xf800
	s_add_i32 s3, s3, s2
	s_mul_i32 s2, s16, 0xf800
	s_waitcnt lgkmcnt(0)
	s_add_u32 s2, s8, s2
	s_addc_u32 s3, s9, s3
	v_lshlrev_b32_e32 v128, 2, v74
	v_lshl_add_u64 v[62:63], s[2:3], 0, v[128:129]
	v_add_co_u32_e32 v8, vcc, s85, v62
	global_load_dwordx2 v[2:3], v128, s[2:3]
	global_load_dwordx2 v[4:5], v128, s[2:3] offset:2048
	v_addc_co_u32_e32 v9, vcc, 0, v63, vcc
	s_movk_i32 s2, 0x2000
	v_add_co_u32_e32 v12, vcc, s2, v62
	s_movk_i32 s2, 0x3000
	s_nop 0
	v_addc_co_u32_e32 v13, vcc, 0, v63, vcc
	v_add_co_u32_e32 v16, vcc, s2, v62
	s_movk_i32 s2, 0x4000
	s_nop 0
	v_addc_co_u32_e32 v17, vcc, 0, v63, vcc
	v_add_co_u32_e32 v20, vcc, s2, v62
	s_movk_i32 s2, 0x5000
	s_nop 0
	v_addc_co_u32_e32 v21, vcc, 0, v63, vcc
	v_add_co_u32_e32 v24, vcc, s2, v62
	s_movk_i32 s2, 0x6000
	s_nop 0
	v_addc_co_u32_e32 v25, vcc, 0, v63, vcc
	v_add_co_u32_e32 v28, vcc, s2, v62
	s_movk_i32 s2, 0x7000
	s_nop 0
	v_addc_co_u32_e32 v29, vcc, 0, v63, vcc
	v_add_co_u32_e32 v32, vcc, s2, v62
	s_mov_b32 s2, 0x8000
	s_nop 0
	v_addc_co_u32_e32 v33, vcc, 0, v63, vcc
	v_add_co_u32_e32 v36, vcc, s2, v62
	s_mov_b32 s2, 0x9000
	s_nop 0
	v_addc_co_u32_e32 v37, vcc, 0, v63, vcc
	v_add_co_u32_e32 v40, vcc, s2, v62
	s_mov_b32 s2, 0xa000
	s_nop 0
	v_addc_co_u32_e32 v41, vcc, 0, v63, vcc
	v_add_co_u32_e32 v44, vcc, s2, v62
	s_mov_b32 s2, 0xb000
	s_nop 0
	v_addc_co_u32_e32 v45, vcc, 0, v63, vcc
	v_add_co_u32_e32 v48, vcc, s2, v62
	s_mov_b32 s2, 0xc000
	s_nop 0
	v_addc_co_u32_e32 v49, vcc, 0, v63, vcc
	v_add_co_u32_e32 v52, vcc, s2, v62
	s_mov_b32 s2, 0xd000
	s_nop 0
	v_addc_co_u32_e32 v53, vcc, 0, v63, vcc
	v_add_co_u32_e32 v56, vcc, s2, v62
	s_mov_b32 s2, 0xe000
	s_nop 0
	v_addc_co_u32_e32 v57, vcc, 0, v63, vcc
	v_add_co_u32_e32 v60, vcc, s2, v62
	s_mov_b32 s2, 0xf000
	s_nop 0
	v_addc_co_u32_e32 v61, vcc, 0, v63, vcc
	s_ashr_i32 s37, s36, 31
	v_add_co_u32_e32 v62, vcc, s2, v62
	s_lshl_b64 s[2:3], s[36:37], 2
	s_add_u32 s6, s10, s2
	s_addc_u32 s7, s11, s3
	global_load_dwordx2 v[6:7], v[12:13], off offset:-4096
	s_nop 0
	global_load_dwordx2 v[8:9], v[8:9], off offset:2048
	s_nop 0
	global_load_dwordx2 v[10:11], v[12:13], off
	s_nop 0
	global_load_dwordx2 v[12:13], v[12:13], off offset:2048
	s_nop 0
	global_load_dwordx2 v[14:15], v[20:21], off offset:-4096
	s_nop 0
	global_load_dwordx2 v[16:17], v[16:17], off offset:2048
	s_nop 0
	global_load_dwordx2 v[18:19], v[20:21], off
	s_nop 0
	global_load_dwordx2 v[20:21], v[20:21], off offset:2048
	s_nop 0
	global_load_dwordx2 v[22:23], v[28:29], off offset:-4096
	s_nop 0
	global_load_dwordx2 v[24:25], v[24:25], off offset:2048
	s_nop 0
	global_load_dwordx2 v[26:27], v[28:29], off
	s_nop 0
	global_load_dwordx2 v[28:29], v[28:29], off offset:2048
	s_nop 0
	global_load_dwordx2 v[30:31], v[36:37], off offset:-4096
	s_nop 0
	global_load_dwordx2 v[32:33], v[32:33], off offset:2048
	s_nop 0
	global_load_dwordx2 v[34:35], v[36:37], off
	s_nop 0
	global_load_dwordx2 v[36:37], v[36:37], off offset:2048
	s_nop 0
	global_load_dwordx2 v[38:39], v[44:45], off offset:-4096
	s_nop 0
	global_load_dwordx2 v[40:41], v[40:41], off offset:2048
	s_nop 0
	global_load_dwordx2 v[42:43], v[44:45], off
	s_nop 0
	global_load_dwordx2 v[44:45], v[44:45], off offset:2048
	s_nop 0
	global_load_dwordx2 v[46:47], v[52:53], off offset:-4096
	s_nop 0
	global_load_dwordx2 v[48:49], v[48:49], off offset:2048
	s_nop 0
	global_load_dwordx2 v[50:51], v[52:53], off
	s_nop 0
	global_load_dwordx2 v[52:53], v[52:53], off offset:2048
	s_nop 0
	global_load_dwordx2 v[54:55], v[60:61], off offset:-4096
	s_nop 0
	global_load_dwordx2 v[56:57], v[56:57], off offset:2048
	s_nop 0
	global_load_dwordx2 v[58:59], v[60:61], off
	s_nop 0
	global_load_dwordx2 v[60:61], v[60:61], off offset:2048
	v_addc_co_u32_e32 v63, vcc, 0, v63, vcc
	global_load_dwordx2 v[64:65], v128, s[6:7]
	s_add_u32 s6, s12, s2
	s_addc_u32 s7, s13, s3
	s_add_u32 s2, s14, s2
	s_addc_u32 s3, s15, s3
	global_load_dwordx2 v[62:63], v[62:63], off
	v_and_b32_e32 v1, 32, v0
	global_load_dwordx2 v[66:67], v128, s[6:7]
	global_load_dwordx2 v[68:69], v128, s[2:3]
	v_cmp_eq_u32_e64 s[6:7], 0, v1
	v_xor_b32_e32 v1, 32, v196
	v_add_u32_e32 v76, 64, v197
	v_and_b32_e32 v77, 16, v0
	v_cmp_lt_i32_e32 vcc, v1, v76
	v_cmp_eq_u32_e64 s[8:9], 0, v77
	v_xor_b32_e32 v77, 16, v196
	v_cndmask_b32_e32 v1, v196, v1, vcc
	v_cmp_lt_i32_e32 vcc, v77, v76
	s_mul_i32 s2, s17, 0x780000
	s_mul_hi_u32 s3, s16, 0x780000
	v_cndmask_b32_e32 v77, v196, v77, vcc
	v_lshlrev_b32_e32 v110, 2, v77
	v_and_b32_e32 v77, 8, v0
	v_cmp_eq_u32_e64 s[10:11], 0, v77
	v_xor_b32_e32 v77, 8, v196
	v_cmp_lt_i32_e32 vcc, v77, v76
	v_lshlrev_b32_e32 v128, 1, v74
	s_add_i32 s20, s3, s2
	v_cndmask_b32_e32 v77, v196, v77, vcc
	v_lshlrev_b32_e32 v111, 2, v77
	v_and_b32_e32 v77, 4, v0
	v_cmp_eq_u32_e64 s[12:13], 0, v77
	v_xor_b32_e32 v77, 4, v196
	v_cmp_lt_i32_e32 vcc, v77, v76
	v_lshl_add_u64 v[72:73], s[74:75], 0, v[128:129]
	s_mov_b64 s[2:3], 0x9280000
	v_cndmask_b32_e32 v77, v196, v77, vcc
	v_lshlrev_b32_e32 v112, 2, v77
	v_xor_b32_e32 v77, 2, v196
	v_cmp_lt_i32_e32 vcc, v77, v76
	v_lshl_add_u64 v[70:71], v[72:73], 0, s[2:3]
	s_mov_b64 s[2:3], 0xc640000
	v_cndmask_b32_e32 v77, v196, v77, vcc
	v_lshlrev_b32_e32 v113, 2, v77
	v_xor_b32_e32 v77, 1, v196
	v_cmp_lt_i32_e32 vcc, v77, v76
	v_lshl_add_u64 v[72:73], v[72:73], 0, s[2:3]
	v_readlane_b32 s2, v254, 14
	v_cndmask_b32_e32 v76, v196, v77, vcc
	v_lshlrev_b32_e32 v114, 2, v76
	v_and_b32_e32 v76, 3, v0
	v_lshlrev_b32_e32 v1, 2, v1
	v_cmp_eq_u32_e64 s[14:15], 0, v76
	v_add_u32_e32 v115, s62, v75
	v_lshlrev_b32_e32 v128, 2, v74
	s_mov_b32 s16, s2
	v_readlane_b32 s21, v254, 13
	v_readlane_b32 s22, v253, 11
	s_sub_i32 s101, 0x1ff, s22
	s_cmp_lt_u32 s101, 48
	s_cbranch_scc1 .Lmxa_none
	s_lshl_b32 s101, s101, 2
	s_cmpk_lt_u32 s101, 0x6e0
	s_cbranch_scc1 .LBB0_270
	s_cmpk_ge_u32 s101, 0x7e0
	s_cbranch_scc1 .LBB0_270
	s_addk_i32 s22, 0x400
	s_addk_i32 s16, 0x4000
	s_addk_i32 s21, 0x800
	s_branch .LBB0_270
; __device__ __forceinline__ unsigned pk2(float lo, float hi) { unsigned r; asm("v_cvt_pk_bf16_f32 %0, %1, %2" : "=v"(r) : "v"(lo), "v"(hi)); return r; }
; __device__ __forceinline__ float silu_f(float x) { return x * sigmoid_f(x); }
; __device__ __forceinline__ void mix_a_wave_jobs(Frame& F, int l) {
;     ...
;         if ((lane & 3) == 0) red[lane >> 2] = (f32x2){r1, r2};
;         asm volatile("s_waitcnt lgkmcnt(0)" ::: "memory");
; #pragma unroll
;         for (int t = 0; t < 16; ++t) {
;             const f32x2 st_ = red[t];
;             const float mean = st_.x * (1.0f / 128.0f), var = st_.y * (1.0f / 128.0f) - mean * mean;
;             const float rstd = __builtin_amdgcn_rsqf(fmaxf(var, 0.f) + EPS);
;             const f32x2 y = (a[t] - mean) * rstd * lgv + lbv;
;             *(unsigned*)(YAB + (size_t)(rowbase + t) * D + c0) = pk2(silu_f(y.x), silu_f(y.y));
.Lmxa_none:
	s_waitcnt vmcnt(0)
	s_branch .LBB0_278
.LBB0_269:
	s_or_b64 exec, exec, s[2:3]
	s_waitcnt lgkmcnt(0)
	v_mov_b32_e32 v131, s62
	s_waitcnt lgkmcnt(0)
	ds_read2_b64 v[106:109], v131 offset1:1
	ds_read2_b64 v[116:119], v131 offset0:2 offset1:3
	ds_read2_b64 v[120:123], v131 offset0:4 offset1:5
	ds_read2_b64 v[124:127], v131 offset0:6 offset1:7
	s_brev_b32 s24, 60
	s_waitcnt lgkmcnt(3)
	v_pk_mul_f32 v[106:107], v[106:107], s[24:25] op_sel_hi:[1,0]
	v_pk_mul_f32 v[108:109], v[108:109], s[24:25] op_sel_hi:[1,0]
	v_fma_f32 v130, -v106, v106, v107
	v_max_f32_e32 v130, 0, v130
	v_add_f32_e32 v130, 0x358637bd, v130
	v_rsq_f32_e32 v130, v130
	v_pk_add_f32 v[74:75], v[74:75], v[106:107] op_sel_hi:[1,0] neg_lo:[0,1] neg_hi:[0,1]
	v_fma_f32 v106, -v108, v108, v109
	v_max_f32_e32 v106, 0, v106
	v_pk_mul_f32 v[74:75], v[74:75], v[130:131] op_sel_hi:[1,0]
	v_add_f32_e32 v106, 0x358637bd, v106
	v_pk_fma_f32 v[74:75], v[66:67], v[74:75], v[68:69]
	v_pk_add_f32 v[76:77], v[76:77], v[108:109] op_sel_hi:[1,0] neg_lo:[0,1] neg_hi:[0,1]
	v_mul_f32_e32 v107, 0xbfb8aa3b, v74
	v_exp_f32_e32 v107, v107
	v_mul_f32_e32 v130, 0xbfb8aa3b, v75
	v_exp_f32_e32 v130, v130
	s_ashr_i32 s19, s18, 31
	v_add_f32_e32 v107, 1.0, v107
	v_rcp_f32_e32 v107, v107
	v_add_f32_e32 v130, 1.0, v130
	v_rcp_f32_e32 v130, v130
	s_lshl_b64 s[2:3], s[18:19], 11
	v_mul_f32_e32 v107, v74, v107
	v_rsq_f32_e32 v74, v106
	v_mul_f32_e32 v75, v75, v130
	v_cvt_pk_bf16_f32 v130, v107, v75
	v_pk_mul_f32 v[74:75], v[76:77], v[74:75] op_sel_hi:[1,0]
	v_pk_fma_f32 v[76:77], v[66:67], v[74:75], v[68:69]
	s_nop 0
	v_mul_f32_e32 v74, 0xbfb8aa3b, v76
	v_exp_f32_e32 v106, v74
	v_lshl_add_u64 v[74:75], v[72:73], 0, s[2:3]
	s_movk_i32 s2, 0x2000
	global_store_dword v[74:75], v130, off
	v_add_f32_e32 v106, 1.0, v106
	v_rcp_f32_e32 v109, v106
	v_mul_f32_e32 v106, 0xbfb8aa3b, v77
	v_exp_f32_e32 v132, v106
	s_waitcnt lgkmcnt(2)
	v_pk_mul_f32 v[106:107], v[116:117], s[24:25] op_sel_hi:[1,0]
	v_mul_f32_e32 v76, v76, v109
	v_fma_f32 v108, -v106, v106, v107
	v_max_f32_e32 v108, 0, v108
	v_add_f32_e32 v108, 0x358637bd, v108
	v_rsq_f32_e32 v108, v108
	v_pk_add_f32 v[78:79], v[78:79], v[106:107] op_sel_hi:[1,0] neg_lo:[0,1] neg_hi:[0,1]
	v_add_f32_e32 v116, 1.0, v132
	v_rcp_f32_e32 v116, v116
	v_pk_mul_f32 v[78:79], v[78:79], v[108:109] op_sel_hi:[1,0]
	v_mul_f32_e32 v77, v77, v116
	v_pk_fma_f32 v[78:79], v[66:67], v[78:79], v[68:69]
	v_cvt_pk_bf16_f32 v76, v76, v77
	global_store_dword v[74:75], v76, off offset:2048
	v_mul_f32_e32 v106, 0xbfb8aa3b, v78
	v_exp_f32_e32 v106, v106
	v_mul_f32_e32 v107, 0xbfb8aa3b, v79
	v_exp_f32_e32 v107, v107
	v_add_f32_e32 v106, 1.0, v106
	v_rcp_f32_e32 v106, v106
	v_add_f32_e32 v76, 1.0, v107
	v_rcp_f32_e32 v107, v76
	v_pk_mul_f32 v[76:77], v[118:119], s[24:25] op_sel_hi:[1,0]
	v_mul_f32_e32 v106, v78, v106
	v_fma_f32 v78, -v76, v76, v77
	v_max_f32_e32 v78, 0, v78
	v_add_f32_e32 v78, 0x358637bd, v78
	v_rsq_f32_e32 v78, v78
	v_mul_f32_e32 v79, v79, v107
	v_pk_add_f32 v[76:77], v[80:81], v[76:77] op_sel_hi:[1,0] neg_lo:[0,1] neg_hi:[0,1]
	v_cvt_pk_bf16_f32 v106, v106, v79
	s_nop 0
	v_pk_mul_f32 v[76:77], v[76:77], v[78:79] op_sel_hi:[1,0]
	s_nop 0
	v_pk_fma_f32 v[76:77], v[66:67], v[76:77], v[68:69]
	s_nop 0
	v_mul_f32_e32 v78, 0xbfb8aa3b, v76
	v_exp_f32_e32 v80, v78
	v_add_co_u32_e32 v78, vcc, s85, v74
	v_add_f32_e32 v80, 1.0, v80
	v_rcp_f32_e32 v107, v80
	v_addc_co_u32_e32 v79, vcc, 0, v75, vcc
	v_add_co_u32_e32 v80, vcc, s2, v74
	v_mul_f32_e32 v108, v76, v107
	s_nop 0
	v_addc_co_u32_e32 v81, vcc, 0, v75, vcc
	global_store_dword v[80:81], v106, off offset:-4096
	v_mul_f32_e32 v76, 0xbfb8aa3b, v77
	s_waitcnt lgkmcnt(1)
	v_pk_mul_f32 v[106:107], v[120:121], s[24:25] op_sel_hi:[1,0]
	v_exp_f32_e32 v109, v76
	v_fma_f32 v76, -v106, v106, v107
	v_max_f32_e32 v76, 0, v76
	v_add_f32_e32 v76, 0x358637bd, v76
	v_rsq_f32_e32 v76, v76
	v_pk_add_f32 v[82:83], v[82:83], v[106:107] op_sel_hi:[1,0] neg_lo:[0,1] neg_hi:[0,1]
	v_add_f32_e32 v109, 1.0, v109
	v_rcp_f32_e32 v109, v109
	v_pk_mul_f32 v[82:83], v[82:83], v[76:77] op_sel_hi:[1,0]
	s_movk_i32 s2, 0x3000
	v_pk_fma_f32 v[82:83], v[66:67], v[82:83], v[68:69]
	v_mul_f32_e32 v77, v77, v109
	v_mul_f32_e32 v76, 0xbfb8aa3b, v82
	v_exp_f32_e32 v76, v76
	v_cvt_pk_bf16_f32 v77, v108, v77
	global_store_dword v[78:79], v77, off offset:2048
	v_add_f32_e32 v76, 1.0, v76
	v_rcp_f32_e32 v79, v76
	v_mul_f32_e32 v76, 0xbfb8aa3b, v83
	v_exp_f32_e32 v106, v76
	v_pk_mul_f32 v[76:77], v[122:123], s[24:25] op_sel_hi:[1,0]
	v_add_f32_e32 v106, 1.0, v106
	v_fma_f32 v78, -v76, v76, v77
	v_max_f32_e32 v78, 0, v78
	v_add_f32_e32 v78, 0x358637bd, v78
	v_rsq_f32_e32 v78, v78
	v_pk_add_f32 v[76:77], v[88:89], v[76:77] op_sel_hi:[1,0] neg_lo:[0,1] neg_hi:[0,1]
	v_rcp_f32_e32 v106, v106
	v_pk_mul_f32 v[76:77], v[76:77], v[78:79] op_sel_hi:[1,0]
	s_nop 0
	v_pk_fma_f32 v[76:77], v[66:67], v[76:77], v[68:69]
	v_mul_f32_e32 v79, v82, v79
	v_mul_f32_e32 v78, 0xbfb8aa3b, v76
	v_exp_f32_e32 v78, v78
	v_mul_f32_e32 v82, v83, v106
	v_cvt_pk_bf16_f32 v83, v79, v82
	global_store_dword v[80:81], v83, off
	v_add_f32_e32 v78, 1.0, v78
	v_rcp_f32_e32 v88, v78
	v_mul_f32_e32 v78, 0xbfb8aa3b, v77
	v_exp_f32_e32 v89, v78
	s_waitcnt lgkmcnt(0)
; __device__ __forceinline__ unsigned pk2(float lo, float hi) { unsigned r; asm("v_cvt_pk_bf16_f32 %0, %1, %2" : "=v"(r) : "v"(lo), "v"(hi)); return r; }
; __device__ __forceinline__ float silu_f(float x) { return x * sigmoid_f(x); }
; __device__ __forceinline__ void mix_a_wave_jobs(Frame& F, int l) {
;     ...
; #pragma unroll
;         for (int t = 0; t < 16; ++t) {
;             const f32x2 st_ = red[t];
;             const float mean = st_.x * (1.0f / 128.0f), var = st_.y * (1.0f / 128.0f) - mean * mean;
;             const float rstd = __builtin_amdgcn_rsqf(fmaxf(var, 0.f) + EPS);
;             const f32x2 y = (a[t] - mean) * rstd * lgv + lbv;
;             *(unsigned*)(YAB + (size_t)(rowbase + t) * D + c0) = pk2(silu_f(y.x), silu_f(y.y));
;         }
	v_pk_mul_f32 v[78:79], v[124:125], s[24:25] op_sel_hi:[1,0]
	v_mul_f32_e32 v76, v76, v88
	v_fma_f32 v82, -v78, v78, v79
	v_max_f32_e32 v82, 0, v82
	v_add_f32_e32 v82, 0x358637bd, v82
	v_rsq_f32_e32 v82, v82
	v_pk_add_f32 v[78:79], v[86:87], v[78:79] op_sel_hi:[1,0] neg_lo:[0,1] neg_hi:[0,1]
	v_add_f32_e32 v89, 1.0, v89
	v_rcp_f32_e32 v89, v89
	v_pk_mul_f32 v[78:79], v[78:79], v[82:83] op_sel_hi:[1,0]
	v_add_co_u32_e32 v86, vcc, s2, v74
	v_pk_fma_f32 v[78:79], v[66:67], v[78:79], v[68:69]
	v_mul_f32_e32 v77, v77, v89
	v_mul_f32_e32 v82, 0xbfb8aa3b, v78
	v_exp_f32_e32 v82, v82
	v_mul_f32_e32 v83, 0xbfb8aa3b, v79
	v_exp_f32_e32 v83, v83
	v_cvt_pk_bf16_f32 v76, v76, v77
	v_add_f32_e32 v82, 1.0, v82
	v_rcp_f32_e32 v82, v82
	global_store_dword v[80:81], v76, off offset:2048
	v_add_f32_e32 v76, 1.0, v83
	v_rcp_f32_e32 v81, v76
	v_pk_mul_f32 v[76:77], v[126:127], s[24:25] op_sel_hi:[1,0]
	v_mul_f32_e32 v80, v78, v82
	v_fma_f32 v78, -v76, v76, v77
	v_max_f32_e32 v78, 0, v78
	v_add_f32_e32 v78, 0x358637bd, v78
	v_rsq_f32_e32 v78, v78
	v_mul_f32_e32 v79, v79, v81
	v_pk_add_f32 v[76:77], v[84:85], v[76:77] op_sel_hi:[1,0] neg_lo:[0,1] neg_hi:[0,1]
	v_cvt_pk_bf16_f32 v79, v80, v79
	v_addc_co_u32_e32 v87, vcc, 0, v75, vcc
	v_pk_mul_f32 v[76:77], v[76:77], v[78:79] op_sel_hi:[1,0]
	s_movk_i32 s2, 0x4000
	v_pk_fma_f32 v[84:85], v[66:67], v[76:77], v[68:69]
	v_add_co_u32_e32 v88, vcc, s2, v74
	v_mul_f32_e32 v76, 0xbfb8aa3b, v84
	v_exp_f32_e32 v76, v76
	v_addc_co_u32_e32 v89, vcc, 0, v75, vcc
	global_store_dword v[88:89], v79, off offset:-4096
	v_add_f32_e32 v76, 1.0, v76
	v_rcp_f32_e32 v80, v76
	ds_read2_b64 v[76:79], v131 offset0:8 offset1:9
	s_movk_i32 s2, 0x5000
	v_mul_f32_e32 v106, v84, v80
	v_mul_f32_e32 v80, 0xbfb8aa3b, v85
	v_exp_f32_e32 v107, v80
	ds_read2_b64 v[80:83], v131 offset0:10 offset1:11
	s_waitcnt lgkmcnt(1)
	v_pk_mul_f32 v[76:77], v[76:77], s[24:25] op_sel_hi:[1,0]
	v_pk_mul_f32 v[78:79], v[78:79], s[24:25] op_sel_hi:[1,0]
	v_fma_f32 v84, -v76, v76, v77
	v_max_f32_e32 v84, 0, v84
	v_add_f32_e32 v84, 0x358637bd, v84
	v_rsq_f32_e32 v84, v84
	v_pk_add_f32 v[76:77], v[90:91], v[76:77] op_sel_hi:[1,0] neg_lo:[0,1] neg_hi:[0,1]
	v_add_f32_e32 v107, 1.0, v107
	v_rcp_f32_e32 v107, v107
	v_pk_mul_f32 v[76:77], v[76:77], v[84:85] op_sel_hi:[1,0]
	v_mul_f32_e32 v85, v85, v107
	v_pk_fma_f32 v[76:77], v[66:67], v[76:77], v[68:69]
	v_cvt_pk_bf16_f32 v85, v106, v85
	global_store_dword v[86:87], v85, off offset:2048
	v_mul_f32_e32 v84, 0xbfb8aa3b, v76
	v_exp_f32_e32 v84, v84
	v_mul_f32_e32 v86, 0xbfb8aa3b, v77
	v_exp_f32_e32 v86, v86
	v_add_f32_e32 v84, 1.0, v84
	v_rcp_f32_e32 v85, v84
	v_fma_f32 v84, -v78, v78, v79
	v_max_f32_e32 v84, 0, v84
	v_add_f32_e32 v84, 0x358637bd, v84
	v_rsq_f32_e32 v84, v84
	v_pk_add_f32 v[78:79], v[92:93], v[78:79] op_sel_hi:[1,0] neg_lo:[0,1] neg_hi:[0,1]
	v_add_f32_e32 v86, 1.0, v86
	v_rcp_f32_e32 v86, v86
	v_pk_mul_f32 v[78:79], v[78:79], v[84:85] op_sel_hi:[1,0]
	v_mul_f32_e32 v76, v76, v85
	v_pk_fma_f32 v[78:79], v[66:67], v[78:79], v[68:69]
	v_mul_f32_e32 v77, v77, v86
	v_mul_f32_e32 v84, 0xbfb8aa3b, v78
	v_exp_f32_e32 v84, v84
	v_cvt_pk_bf16_f32 v76, v76, v77
	global_store_dword v[88:89], v76, off
	v_mul_f32_e32 v76, 0xbfb8aa3b, v79
	v_add_f32_e32 v84, 1.0, v84
	v_rcp_f32_e32 v84, v84
	v_exp_f32_e32 v85, v76
	s_waitcnt lgkmcnt(0)
	v_pk_mul_f32 v[76:77], v[80:81], s[24:25] op_sel_hi:[1,0]
	v_mul_f32_e32 v84, v78, v84
	v_fma_f32 v78, -v76, v76, v77
	v_max_f32_e32 v78, 0, v78
	v_add_f32_e32 v78, 0x358637bd, v78
	v_rsq_f32_e32 v78, v78
	v_pk_add_f32 v[76:77], v[94:95], v[76:77] op_sel_hi:[1,0] neg_lo:[0,1] neg_hi:[0,1]
	v_add_f32_e32 v80, 1.0, v85
	v_rcp_f32_e32 v80, v80
	v_pk_mul_f32 v[76:77], v[76:77], v[78:79] op_sel_hi:[1,0]
	v_mul_f32_e32 v79, v79, v80
	v_pk_fma_f32 v[76:77], v[66:67], v[76:77], v[68:69]
	v_cvt_pk_bf16_f32 v79, v84, v79
	global_store_dword v[88:89], v79, off offset:2048
	v_mul_f32_e32 v78, 0xbfb8aa3b, v76
	v_mul_f32_e32 v81, 0xbfb8aa3b, v77
	v_exp_f32_e32 v78, v78
	v_exp_f32_e32 v81, v81
	v_add_co_u32_e32 v84, vcc, s2, v74
	v_add_f32_e32 v78, 1.0, v78
	v_add_f32_e32 v80, 1.0, v81
	v_rcp_f32_e32 v78, v78
	v_rcp_f32_e32 v80, v80
	v_addc_co_u32_e32 v85, vcc, 0, v75, vcc
	v_mul_f32_e32 v76, v76, v78
	v_mul_f32_e32 v77, v77, v80
	v_cvt_pk_bf16_f32 v79, v76, v77
	v_pk_mul_f32 v[76:77], v[82:83], s[24:25] op_sel_hi:[1,0]
	s_movk_i32 s2, 0x6000
	v_fma_f32 v78, -v76, v76, v77
	v_max_f32_e32 v78, 0, v78
	v_add_f32_e32 v78, 0x358637bd, v78
	v_rsq_f32_e32 v78, v78
	v_pk_add_f32 v[76:77], v[98:99], v[76:77] op_sel_hi:[1,0] neg_lo:[0,1] neg_hi:[0,1]
	v_add_co_u32_e32 v88, vcc, s2, v74
	v_pk_mul_f32 v[76:77], v[76:77], v[78:79] op_sel_hi:[1,0]
	s_nop 0
	v_addc_co_u32_e32 v89, vcc, 0, v75, vcc
	v_pk_fma_f32 v[86:87], v[66:67], v[76:77], v[68:69]
	global_store_dword v[88:89], v79, off offset:-4096
	v_mul_f32_e32 v76, 0xbfb8aa3b, v86
	v_exp_f32_e32 v76, v76
	s_movk_i32 s2, 0x7000
	v_add_co_u32_e32 v74, vcc, s2, v74
	v_add_f32_e32 v80, 1.0, v76
	ds_read2_b64 v[76:79], v131 offset0:12 offset1:13
	v_rcp_f32_e32 v91, v80
	v_mul_f32_e32 v80, 0xbfb8aa3b, v87
	v_exp_f32_e32 v92, v80
	ds_read2_b64 v[80:83], v131 offset0:14 offset1:15
	s_waitcnt lgkmcnt(1)
; __device__ __forceinline__ unsigned pk2(float lo, float hi) { unsigned r; asm("v_cvt_pk_bf16_f32 %0, %1, %2" : "=v"(r) : "v"(lo), "v"(hi)); return r; }
; __device__ __forceinline__ float silu_f(float x) { return x * sigmoid_f(x); }
; __device__ __forceinline__ void mix_a_wave_jobs(Frame& F, int l) {
;     ...
;     for (int tb = 511 - ((int)blockIdx.x * 2 + (wave >> 2)); tb < 1096; tb += 512) {
;     ...
; #pragma unroll
;         for (int t = 0; t < 16; ++t) {
;             const f32x2 st_ = red[t];
;             const float mean = st_.x * (1.0f / 128.0f), var = st_.y * (1.0f / 128.0f) - mean * mean;
;             const float rstd = __builtin_amdgcn_rsqf(fmaxf(var, 0.f) + EPS);
;             const f32x2 y = (a[t] - mean) * rstd * lgv + lbv;
;             *(unsigned*)(YAB + (size_t)(rowbase + t) * D + c0) = pk2(silu_f(y.x), silu_f(y.y));
;         }
;         asm volatile("s_waitcnt lgkmcnt(0)" ::: "memory");
;     }
	v_pk_mul_f32 v[76:77], v[76:77], s[24:25] op_sel_hi:[1,0]
	v_mul_f32_e32 v86, v86, v91
	v_fma_f32 v90, -v76, v76, v77
	v_max_f32_e32 v90, 0, v90
	v_add_f32_e32 v90, 0x358637bd, v90
	v_rsq_f32_e32 v90, v90
	v_pk_add_f32 v[76:77], v[96:97], v[76:77] op_sel_hi:[1,0] neg_lo:[0,1] neg_hi:[0,1]
	v_add_f32_e32 v92, 1.0, v92
	v_rcp_f32_e32 v92, v92
	v_pk_mul_f32 v[76:77], v[76:77], v[90:91] op_sel_hi:[1,0]
	v_pk_mul_f32 v[78:79], v[78:79], s[24:25] op_sel_hi:[1,0]
	v_pk_fma_f32 v[76:77], v[66:67], v[76:77], v[68:69]
	v_mul_f32_e32 v87, v87, v92
	v_mul_f32_e32 v90, 0xbfb8aa3b, v76
	v_exp_f32_e32 v90, v90
	v_cvt_pk_bf16_f32 v87, v86, v87
	global_store_dword v[84:85], v87, off offset:2048
	v_addc_co_u32_e32 v75, vcc, 0, v75, vcc
	v_add_f32_e32 v86, 1.0, v90
	v_rcp_f32_e32 v90, v86
	v_mul_f32_e32 v86, 0xbfb8aa3b, v77
	v_exp_f32_e32 v91, v86
	v_fma_f32 v86, -v78, v78, v79
	v_max_f32_e32 v86, 0, v86
	v_add_f32_e32 v86, 0x358637bd, v86
	v_rsq_f32_e32 v86, v86
	v_pk_add_f32 v[78:79], v[100:101], v[78:79] op_sel_hi:[1,0] neg_lo:[0,1] neg_hi:[0,1]
	v_add_f32_e32 v91, 1.0, v91
	v_rcp_f32_e32 v91, v91
	v_pk_mul_f32 v[78:79], v[78:79], v[86:87] op_sel_hi:[1,0]
	v_mul_f32_e32 v76, v76, v90
	v_pk_fma_f32 v[78:79], v[66:67], v[78:79], v[68:69]
	v_mul_f32_e32 v77, v77, v91
	v_mul_f32_e32 v86, 0xbfb8aa3b, v78
	v_exp_f32_e32 v86, v86
	v_mul_f32_e32 v85, 0xbfb8aa3b, v79
	v_exp_f32_e32 v85, v85
	v_cvt_pk_bf16_f32 v76, v76, v77
	v_add_f32_e32 v84, 1.0, v86
	v_rcp_f32_e32 v84, v84
	global_store_dword v[88:89], v76, off
	v_add_f32_e32 v76, 1.0, v85
	v_rcp_f32_e32 v85, v76
	s_waitcnt lgkmcnt(0)
	v_pk_mul_f32 v[76:77], v[80:81], s[24:25] op_sel_hi:[1,0]
	v_mul_f32_e32 v84, v78, v84
	v_fma_f32 v78, -v76, v76, v77
	v_max_f32_e32 v78, 0, v78
	v_add_f32_e32 v78, 0x358637bd, v78
	v_rsq_f32_e32 v78, v78
	v_mul_f32_e32 v79, v79, v85
	v_pk_add_f32 v[76:77], v[102:103], v[76:77] op_sel_hi:[1,0] neg_lo:[0,1] neg_hi:[0,1]
	v_cvt_pk_bf16_f32 v79, v84, v79
	global_store_dword v[88:89], v79, off offset:2048
	v_pk_mul_f32 v[76:77], v[76:77], v[78:79] op_sel_hi:[1,0]
	v_pk_fma_f32 v[76:77], v[66:67], v[76:77], v[68:69]
	v_mul_f32_e32 v78, 0xbfb8aa3b, v76
	v_exp_f32_e32 v78, v78
	v_mul_f32_e32 v80, 0xbfb8aa3b, v77
	v_exp_f32_e32 v80, v80
	v_add_f32_e32 v78, 1.0, v78
	v_rcp_f32_e32 v81, v78
	v_add_f32_e32 v78, 1.0, v80
	v_rcp_f32_e32 v84, v78
	v_pk_mul_f32 v[78:79], v[82:83], s[24:25] op_sel_hi:[1,0]
	v_mul_f32_e32 v81, v76, v81
	v_fma_f32 v80, -v78, v78, v79
	v_max_f32_e32 v80, 0, v80
	v_add_f32_e32 v80, 0x358637bd, v80
	v_rsq_f32_e32 v80, v80
	v_mul_f32_e32 v82, v77, v84
	v_pk_add_f32 v[76:77], v[104:105], v[78:79] op_sel_hi:[1,0] neg_lo:[0,1] neg_hi:[0,1]
	s_nop 0
	v_pk_mul_f32 v[76:77], v[76:77], v[80:81] op_sel_hi:[1,0]
	v_cvt_pk_bf16_f32 v80, v81, v82
	global_store_dword v[74:75], v80, off
	v_pk_fma_f32 v[76:77], v[66:67], v[76:77], v[68:69]
	s_nop 0
	v_mul_f32_e32 v78, 0xbfb8aa3b, v76
	v_exp_f32_e32 v78, v78
	v_mul_f32_e32 v79, 0xbfb8aa3b, v77
	v_exp_f32_e32 v79, v79
	v_add_f32_e32 v78, 1.0, v78
	v_rcp_f32_e32 v78, v78
	v_add_f32_e32 v79, 1.0, v79
	v_rcp_f32_e32 v79, v79
	v_mul_f32_e32 v76, v76, v78
	v_mul_f32_e32 v77, v77, v79
	v_cvt_pk_bf16_f32 v76, v76, v77
	global_store_dword v[74:75], v76, off offset:2048
	s_waitcnt lgkmcnt(0)
	s_add_i32 s101, s101, 1
	s_lshr_b32 s2, s101, 2
	s_and_b32 s3, s101, 3
	s_cmpk_ge_u32 s2, 0x1b8
	s_cbranch_scc1 .Lmxa_bc
	s_cmp_eq_u32 s3, 1
	s_cbranch_scc1 .Lmxa_p512
	s_cmp_eq_u32 s3, 2
	s_cbranch_scc0 .LBB0_278
	s_sub_i32 s2, s2, 48
	s_cmpk_ge_u32 s2, 0xe0
	s_cbranch_scc1 .LBB0_278
	s_add_i32 s22, s2, 0x1d0
	s_cmp_lt_u32 s2, 48
	s_cbranch_scc1 .Lmxa_set
	s_add_i32 s22, s2, 0x3a0
	s_cmpk_lt_u32 s2, 0x60
	s_cbranch_scc1 .Lmxa_set
	s_add_i32 s22, s2, -88
	s_cmpk_lt_u32 s2, 0xa0
	s_cbranch_scc1 .Lmxa_set
	s_add_i32 s22, s2, 0x168
.Lmxa_set:
	s_lshl_b32 s16, s22, 4
	s_add_i32 s16, s16, 15
	s_lshl_b32 s21, s22, 1
	s_addk_i32 s21, 0xf7f0
	s_branch .LBB0_270
.Lmxa_bc:
	s_cmpk_lt_u32 s2, 0x1f8
	s_cbranch_scc1 .LBB0_278
	s_cmp_ge_u32 s3, 3
	s_cbranch_scc1 .LBB0_278
.Lmxa_p512:
	s_addk_i32 s22, 0x200
	s_addk_i32 s16, 0x2000
	s_addk_i32 s21, 0x400

; __global__ void __launch_bounds__(NWAVES * 64, 2) mega_fwd(Args args) {
	.amdhsa_kernel _Z8mega_fwd4Args
		.amdhsa_group_segment_fixed_size 0
		.amdhsa_private_segment_fixed_size 0
		.amdhsa_kernarg_size 512
		.amdhsa_user_sgpr_count 2
		.amdhsa_user_sgpr_dispatch_ptr 0
		.amdhsa_user_sgpr_queue_ptr 0
		.amdhsa_user_sgpr_kernarg_segment_ptr 1
		.amdhsa_user_sgpr_dispatch_id 0
		.amdhsa_user_sgpr_kernarg_preload_length 0
		.amdhsa_user_sgpr_kernarg_preload_offset 0
		.amdhsa_user_sgpr_private_segment_size 0
		.amdhsa_uses_dynamic_stack 0
		.amdhsa_enable_private_segment 0
		.amdhsa_system_sgpr_workgroup_id_x 1
		.amdhsa_system_sgpr_workgroup_id_y 0
		.amdhsa_system_sgpr_workgroup_id_z 0
		.amdhsa_system_sgpr_workgroup_info 0
		.amdhsa_system_vgpr_workitem_id 2
		.amdhsa_next_free_vgpr 256
		.amdhsa_next_free_sgpr 102
		.amdhsa_accum_offset 256
		.amdhsa_reserve_vcc 1
		.amdhsa_float_round_mode_32 0
		.amdhsa_float_round_mode_16_64 0
		.amdhsa_float_denorm_mode_32 3
		.amdhsa_float_denorm_mode_16_64 3
		.amdhsa_dx10_clamp 1
		.amdhsa_ieee_mode 1
		.amdhsa_fp16_overflow 0
		.amdhsa_tg_split 0
		.amdhsa_exception_fp_ieee_invalid_op 0
		.amdhsa_exception_fp_denorm_src 0
		.amdhsa_exception_fp_ieee_div_zero 0
		.amdhsa_exception_fp_ieee_overflow 0
		.amdhsa_exception_fp_ieee_underflow 0
		.amdhsa_exception_fp_ieee_inexact 0
		.amdhsa_exception_int_div_zero 0
	.end_amdhsa_kernel

; __global__ void __launch_bounds__(NWAVES * 64, 2) mega_fwd(Args args) {
amdhsa.kernels:
  - .agpr_count:     0
    .args:
      - .offset:         0
        .size:           256
        .value_kind:     by_value
      - .offset:         256
        .size:           4
        .value_kind:     hidden_block_count_x
      - .offset:         260
        .size:           4
        .value_kind:     hidden_block_count_y
      - .offset:         264
        .size:           4
        .value_kind:     hidden_block_count_z
      - .offset:         268
        .size:           2
        .value_kind:     hidden_group_size_x
      - .offset:         270
        .size:           2
        .value_kind:     hidden_group_size_y
      - .offset:         272
        .size:           2
        .value_kind:     hidden_group_size_z
      - .offset:         274
        .size:           2
        .value_kind:     hidden_remainder_x
      - .offset:         276
        .size:           2
        .value_kind:     hidden_remainder_y
      - .offset:         278
        .size:           2
        .value_kind:     hidden_remainder_z
      - .offset:         296
        .size:           8
        .value_kind:     hidden_global_offset_x
      - .offset:         304
        .size:           8
        .value_kind:     hidden_global_offset_y
      - .offset:         312
        .size:           8
        .value_kind:     hidden_global_offset_z
      - .offset:         320
        .size:           2
        .value_kind:     hidden_grid_dims
      - .offset:         344
        .size:           8
        .value_kind:     hidden_multigrid_sync_arg
      - .offset:         376
        .size:           4
        .value_kind:     hidden_dynamic_lds_size
    .group_segment_fixed_size: 0
    .kernarg_segment_align: 8
    .kernarg_segment_size: 512
    .language:       OpenCL C
    .language_version:
      - 2
      - 0
    .max_flat_workgroup_size: 512
    .name:           _Z8mega_fwd4Args
    .private_segment_fixed_size: 0
    .sgpr_count:     108
    .sgpr_spill_count: 171
    .symbol:         _Z8mega_fwd4Args.kd
    .uniform_work_group_size: 1
    .uses_dynamic_stack: false
    .vgpr_count:     256
    .vgpr_spill_count: 0
    .wavefront_size: 64
